# fast body re-enters itself directly: next step near/far decision computed in the tail under the P-write latency, dispatcher only on general->fast transitions
# speedup vs baseline: 1.0005x; 1.0005x over previous
; #define DMAWAIT() asm volatile("s_waitcnt vmcnt(0)" ::: "memory")
; #define SMX_FIN(pbuf) do { _Pragma("unroll") for (int r = 0; r < 16; ++r) l_reg += S[r]; \
;     PK4S(0, po0); PK4S(8, po1); \
;     *(bf16x8*)(pw + (pbuf) * 16384) = po0; *(bf16x8*)(pw + (pbuf) * 16384 + 16) = po1; } while (0)
; #define VRD(D0, X) do { X##0 = tr_read<v_rd_off(D0, 0, 0)>(vb); X##1 = tr_read<v_rd_off(D0, 0, 1)>(vb); X##2 = tr_read<v_rd_off(D0, 1, 0)>(vb); X##3 = tr_read<v_rd_off(D0, 1, 1)>(vb); \
;     X##4 = tr_read<v_rd_off(D0, 2, 0)>(vb); X##5 = tr_read<v_rd_off(D0, 2, 1)>(vb); X##6 = tr_read<v_rd_off(D0, 3, 0)>(vb); X##7 = tr_read<v_rd_off(D0, 3, 1)>(vb); } while (0)
; #define LWAIT() do { asm volatile("s_waitcnt lgkmcnt(0)" ::: "memory"); SBAR(); } while (0)
; #define VMMP(D0, X) do { if (!(PROBE & 8)) VMM(D0, X); } while (0)
; #define SMXP(c) do { if (!(PROBE & 2)) { if (more) SMX_CH(c); } } while (0)
; template <int PROBE, int MODE>
; DI void dattn_body(const u16* __restrict__ Qb, const u16* __restrict__ Kh, const u16* __restrict__ Vh, u16* __restrict__ Ob, const u16* __restrict__ O1, float lam, const float* __restrict__ subg, int seq, int q0, float kmax2, char* lds) {
;     ...
;     LWAIT(); VRD(1, vc); VMMP(0, va); SMXP(0);
;     LWAIT(); VRD(2, va); VMMP(1, vc); SMXP(1);
;     LWAIT(); VRD(3, vc); VMMP(2, va); SMXP(2);
;     LWAIT(); VMMP(3, vc); SMXP(3);
;     if (!(PROBE & 2)) { if (more) SMX_FIN((j + 1) & 1); }
;     DMAWAIT();
;     __syncthreads();
.Lfast0_k_done:
	s_waitcnt lgkmcnt(6)
	v_mfma_f32_32x32x16_bf16 v[0:15], v[114:117], v[234:237], v[0:15]
	ds_read_b64_tr_b16 v[138:139], v216 offset:0x200
	ds_read_b64_tr_b16 v[140:141], v216 offset:0xa00
	s_waitcnt lgkmcnt(6)
	v_mfma_f32_32x32x16_bf16 v[0:15], v[130:133], v[238:241], v[0:15]
	ds_read_b64_tr_b16 v[142:143], v216 offset:0x1200
	ds_read_b64_tr_b16 v[144:145], v216 offset:0x1a00
	s_nop 1
	v_fma_f32 v118, v64, s12, v160
	v_fma_f32 v119, v65, s12, v160
	v_fma_f32 v120, v66, s12, v160
	v_fma_f32 v121, v67, s12, v160
	s_waitcnt lgkmcnt(6)
	v_mfma_f32_32x32x16_bf16 v[0:15], v[162:165], v[242:245], v[0:15]
	ds_read_b64_tr_b16 v[134:135], v233 offset:0x2200
	ds_read_b64_tr_b16 v[136:137], v233 offset:0x2a00
	v_fma_f32 v122, v68, s12, v160
	v_fma_f32 v123, v69, s12, v160
	v_exp_f32_e32 v118, v118
	v_exp_f32_e32 v119, v119
	s_waitcnt lgkmcnt(6)
	v_mfma_f32_32x32x16_bf16 v[0:15], v[166:169], v[246:249], v[0:15]
	ds_read_b64_tr_b16 v[126:127], v233 offset:0x3200
	ds_read_b64_tr_b16 v[128:129], v233 offset:0x3a00
	v_fma_f32 v124, v70, s12, v160
	v_fma_f32 v125, v71, s12, v160
	v_exp_f32_e32 v120, v120
	v_exp_f32_e32 v121, v121
	s_waitcnt lgkmcnt(6)
	v_mfma_f32_32x32x16_bf16 v[16:31], v[114:117], v[138:141], v[16:31]
	ds_read_b64_tr_b16 v[146:147], v216 offset:0x400
	ds_read_b64_tr_b16 v[148:149], v216 offset:0xc00
	v_exp_f32_e32 v122, v122
	v_exp_f32_e32 v123, v123
	v_add_f32_e32 v209, v118, v209
	v_add_f32_e32 v209, v119, v209
	s_waitcnt lgkmcnt(6)
	v_mfma_f32_32x32x16_bf16 v[16:31], v[130:133], v[142:145], v[16:31]
	ds_read_b64_tr_b16 v[142:143], v216 offset:0x1400
	ds_read_b64_tr_b16 v[144:145], v216 offset:0x1c00
	v_exp_f32_e32 v124, v124
	v_exp_f32_e32 v125, v125
	v_add_f32_e32 v209, v120, v209
	v_add_f32_e32 v209, v121, v209
	v_fma_f32 v244, v72, s12, v160
	v_fma_f32 v245, v73, s12, v160
	s_waitcnt lgkmcnt(6)
	v_mfma_f32_32x32x16_bf16 v[16:31], v[162:165], v[134:137], v[16:31]
	ds_read_b64_tr_b16 v[138:139], v233 offset:0x2400
	ds_read_b64_tr_b16 v[140:141], v233 offset:0x2c00
	v_fma_f32 v246, v74, s12, v160
	v_fma_f32 v247, v75, s12, v160
	v_add_f32_e32 v209, v122, v209
	v_add_f32_e32 v209, v123, v209
	s_waitcnt lgkmcnt(6)
	v_mfma_f32_32x32x16_bf16 v[16:31], v[166:169], v[126:129], v[16:31]
	ds_read_b64_tr_b16 v[64:65], v233 offset:0x3400
	ds_read_b64_tr_b16 v[66:67], v233 offset:0x3c00
	v_fma_f32 v76, v76, s12, v160
	v_fma_f32 v77, v77, s12, v160
	v_fma_f32 v78, v78, s12, v160
	v_fma_f32 v79, v79, s12, v160
	s_waitcnt lgkmcnt(6)
	v_mfma_f32_32x32x16_bf16 v[32:47], v[114:117], v[146:149], v[32:47]
	v_exp_f32_e32 v244, v244
	v_exp_f32_e32 v245, v245
	v_add_f32_e32 v209, v124, v209
	v_add_f32_e32 v209, v125, v209
	s_waitcnt lgkmcnt(4)
	v_mfma_f32_32x32x16_bf16 v[32:47], v[130:133], v[142:145], v[32:47]
	ds_read_b64_tr_b16 v[142:143], v216 offset:0x600
	ds_read_b64_tr_b16 v[144:145], v216 offset:0xe00
	ds_read_b64_tr_b16 v[126:127], v216 offset:0x1600
	ds_read_b64_tr_b16 v[128:129], v216 offset:0x1e00
	v_exp_f32_e32 v246, v246
	v_exp_f32_e32 v247, v247
	s_waitcnt lgkmcnt(6)
	v_mfma_f32_32x32x16_bf16 v[32:47], v[162:165], v[138:141], v[32:47]
	ds_read_b64_tr_b16 v[134:135], v233 offset:0x2600
	ds_read_b64_tr_b16 v[136:137], v233 offset:0x2e00
	v_exp_f32_e32 v76, v76
	v_exp_f32_e32 v77, v77
	v_add_f32_e32 v209, v244, v209
	v_add_f32_e32 v209, v245, v209
	s_waitcnt lgkmcnt(6)
	v_mfma_f32_32x32x16_bf16 v[32:47], v[166:169], v[64:67], v[32:47]
	ds_read_b64_tr_b16 v[68:69], v233 offset:0x3600
	ds_read_b64_tr_b16 v[70:71], v233 offset:0x3e00
	v_exp_f32_e32 v78, v78
	v_exp_f32_e32 v79, v79
	v_add_f32_e32 v209, v246, v209
	v_add_f32_e32 v209, v247, v209
	s_waitcnt lgkmcnt(6)
	v_mfma_f32_32x32x16_bf16 v[48:63], v[114:117], v[142:145], v[48:63]
	v_add_u32_e32 v64, s19, v211
	v_add_f32_e32 v209, v76, v209
	v_add_f32_e32 v209, v77, v209
	v_cvt_pk_bf16_f32 v114, v118, v119
	v_cvt_pk_bf16_f32 v115, v120, v121
	v_cvt_pk_bf16_f32 v116, v122, v123
	v_cvt_pk_bf16_f32 v117, v124, v125
	s_waitcnt lgkmcnt(4)
	v_mfma_f32_32x32x16_bf16 v[48:63], v[130:133], v[126:129], v[48:63]
	v_add_f32_e32 v209, v78, v209
	v_add_f32_e32 v209, v79, v209
	v_permlane32_swap_b32_e32 v114, v116
	v_permlane32_swap_b32_e32 v115, v117
	v_cvt_pk_bf16_f32 v130, v244, v245
	v_cvt_pk_bf16_f32 v131, v246, v247
	v_cvt_pk_bf16_f32 v132, v76, v77
	v_cvt_pk_bf16_f32 v133, v78, v79
	ds_write_b128 v64, v[114:117]
	s_nop 0
	v_permlane32_swap_b32_e32 v130, v132
	v_permlane32_swap_b32_e32 v131, v133
	ds_write_b128 v64, v[130:133] offset:16
	s_add_i32 s55, s55, 1
	s_add_i32 s18, s18, 64
	s_add_i32 s54, s54, 0x8000
	s_add_i32 s100, s18, -1
	s_cmp_ge_i32 s100, s33
	s_cselect_b32 s100, 1, 0
	s_sub_i32 s101, s18, 64
	s_cmp_le_i32 s101, s35
	s_cselect_b32 s101, 1, 0
	s_and_b32 s100, s100, s101
	s_cmp_eq_u32 s83, s55
	s_waitcnt vmcnt(0) lgkmcnt(0)
	s_barrier
	v_mfma_f32_32x32x16_bf16 v[48:63], v[162:165], v[134:137], v[48:63]
	v_mfma_f32_32x32x16_bf16 v[48:63], v[166:169], v[68:71], v[48:63]
	s_cbranch_scc1 .LBB0_265
	s_cmp_lg_u32 s100, 0
	s_cbranch_scc1 .Lgen0
	s_branch .Lfast0

; #define DMAWAIT() asm volatile("s_waitcnt vmcnt(0)" ::: "memory")
; #define SMX_FIN(pbuf) do { _Pragma("unroll") for (int r = 0; r < 16; ++r) l_reg += S[r]; \
;     PK4S(0, po0); PK4S(8, po1); \
;     *(bf16x8*)(pw + (pbuf) * 16384) = po0; *(bf16x8*)(pw + (pbuf) * 16384 + 16) = po1; } while (0)
; #define VRD(D0, X) do { X##0 = tr_read<v_rd_off(D0, 0, 0)>(vb); X##1 = tr_read<v_rd_off(D0, 0, 1)>(vb); X##2 = tr_read<v_rd_off(D0, 1, 0)>(vb); X##3 = tr_read<v_rd_off(D0, 1, 1)>(vb); \
;     X##4 = tr_read<v_rd_off(D0, 2, 0)>(vb); X##5 = tr_read<v_rd_off(D0, 2, 1)>(vb); X##6 = tr_read<v_rd_off(D0, 3, 0)>(vb); X##7 = tr_read<v_rd_off(D0, 3, 1)>(vb); } while (0)
; #define LWAIT() do { asm volatile("s_waitcnt lgkmcnt(0)" ::: "memory"); SBAR(); } while (0)
; #define VMMP(D0, X) do { if (!(PROBE & 8)) VMM(D0, X); } while (0)
; #define SMXP(c) do { if (!(PROBE & 2)) { if (more) SMX_CH(c); } } while (0)
; template <int PROBE, int MODE>
; DI void dattn_body(const u16* __restrict__ Qb, const u16* __restrict__ Kh, const u16* __restrict__ Vh, u16* __restrict__ Ob, const u16* __restrict__ O1, float lam, const float* __restrict__ subg, int seq, int q0, float kmax2, char* lds) {
;     ...
;     LWAIT(); VRD(1, vc); VMMP(0, va); SMXP(0);
;     LWAIT(); VRD(2, va); VMMP(1, vc); SMXP(1);
;     LWAIT(); VRD(3, vc); VMMP(2, va); SMXP(2);
;     LWAIT(); VMMP(3, vc); SMXP(3);
;     if (!(PROBE & 2)) { if (more) SMX_FIN((j + 1) & 1); }
;     DMAWAIT();
;     __syncthreads();
.Lfast1_k_done:
	s_waitcnt lgkmcnt(6)
	v_mfma_f32_32x32x16_bf16 v[0:15], v[114:117], v[234:237], v[0:15]
	ds_read_b64_tr_b16 v[138:139], v215 offset:0x200
	ds_read_b64_tr_b16 v[140:141], v215 offset:0xa00
	s_waitcnt lgkmcnt(6)
	v_mfma_f32_32x32x16_bf16 v[0:15], v[130:133], v[238:241], v[0:15]
	ds_read_b64_tr_b16 v[142:143], v215 offset:0x1200
	ds_read_b64_tr_b16 v[144:145], v215 offset:0x1a00
	s_nop 1
	v_fma_f32 v118, v64, s12, v160
	v_fma_f32 v119, v65, s12, v160
	v_fma_f32 v120, v66, s12, v160
	v_fma_f32 v121, v67, s12, v160
	s_waitcnt lgkmcnt(6)
	v_mfma_f32_32x32x16_bf16 v[0:15], v[162:165], v[242:245], v[0:15]
	ds_read_b64_tr_b16 v[134:135], v233 offset:0x2200
	ds_read_b64_tr_b16 v[136:137], v233 offset:0x2a00
	v_fma_f32 v122, v68, s12, v160
	v_fma_f32 v123, v69, s12, v160
	v_exp_f32_e32 v118, v118
	v_exp_f32_e32 v119, v119
	s_waitcnt lgkmcnt(6)
	v_mfma_f32_32x32x16_bf16 v[0:15], v[166:169], v[246:249], v[0:15]
	ds_read_b64_tr_b16 v[126:127], v233 offset:0x3200
	ds_read_b64_tr_b16 v[128:129], v233 offset:0x3a00
	v_fma_f32 v124, v70, s12, v160
	v_fma_f32 v125, v71, s12, v160
	v_exp_f32_e32 v120, v120
	v_exp_f32_e32 v121, v121
	s_waitcnt lgkmcnt(6)
	v_mfma_f32_32x32x16_bf16 v[16:31], v[114:117], v[138:141], v[16:31]
	ds_read_b64_tr_b16 v[146:147], v215 offset:0x400
	ds_read_b64_tr_b16 v[148:149], v215 offset:0xc00
	v_exp_f32_e32 v122, v122
	v_exp_f32_e32 v123, v123
	v_add_f32_e32 v208, v118, v208
	v_add_f32_e32 v208, v119, v208
	s_waitcnt lgkmcnt(6)
	v_mfma_f32_32x32x16_bf16 v[16:31], v[130:133], v[142:145], v[16:31]
	ds_read_b64_tr_b16 v[142:143], v215 offset:0x1400
	ds_read_b64_tr_b16 v[144:145], v215 offset:0x1c00
	v_exp_f32_e32 v124, v124
	v_exp_f32_e32 v125, v125
	v_add_f32_e32 v208, v120, v208
	v_add_f32_e32 v208, v121, v208
	v_fma_f32 v244, v72, s12, v160
	v_fma_f32 v245, v73, s12, v160
	s_waitcnt lgkmcnt(6)
	v_mfma_f32_32x32x16_bf16 v[16:31], v[162:165], v[134:137], v[16:31]
	ds_read_b64_tr_b16 v[138:139], v233 offset:0x2400
	ds_read_b64_tr_b16 v[140:141], v233 offset:0x2c00
	v_fma_f32 v246, v74, s12, v160
	v_fma_f32 v247, v75, s12, v160
	v_add_f32_e32 v208, v122, v208
	v_add_f32_e32 v208, v123, v208
	s_waitcnt lgkmcnt(6)
	v_mfma_f32_32x32x16_bf16 v[16:31], v[166:169], v[126:129], v[16:31]
	ds_read_b64_tr_b16 v[64:65], v233 offset:0x3400
	ds_read_b64_tr_b16 v[66:67], v233 offset:0x3c00
	v_fma_f32 v76, v76, s12, v160
	v_fma_f32 v77, v77, s12, v160
	v_fma_f32 v78, v78, s12, v160
	v_fma_f32 v79, v79, s12, v160
	s_waitcnt lgkmcnt(6)
	v_mfma_f32_32x32x16_bf16 v[32:47], v[114:117], v[146:149], v[32:47]
	v_exp_f32_e32 v244, v244
	v_exp_f32_e32 v245, v245
	v_add_f32_e32 v208, v124, v208
	v_add_f32_e32 v208, v125, v208
	s_waitcnt lgkmcnt(4)
	v_mfma_f32_32x32x16_bf16 v[32:47], v[130:133], v[142:145], v[32:47]
	ds_read_b64_tr_b16 v[142:143], v215 offset:0x600
	ds_read_b64_tr_b16 v[144:145], v215 offset:0xe00
	ds_read_b64_tr_b16 v[126:127], v215 offset:0x1600
	ds_read_b64_tr_b16 v[128:129], v215 offset:0x1e00
	v_exp_f32_e32 v246, v246
	v_exp_f32_e32 v247, v247
	s_waitcnt lgkmcnt(6)
	v_mfma_f32_32x32x16_bf16 v[32:47], v[162:165], v[138:141], v[32:47]
	ds_read_b64_tr_b16 v[134:135], v233 offset:0x2600
	ds_read_b64_tr_b16 v[136:137], v233 offset:0x2e00
	v_exp_f32_e32 v76, v76
	v_exp_f32_e32 v77, v77
	v_add_f32_e32 v208, v244, v208
	v_add_f32_e32 v208, v245, v208
	s_waitcnt lgkmcnt(6)
	v_mfma_f32_32x32x16_bf16 v[32:47], v[166:169], v[64:67], v[32:47]
	ds_read_b64_tr_b16 v[68:69], v233 offset:0x3600
	ds_read_b64_tr_b16 v[70:71], v233 offset:0x3e00
	v_exp_f32_e32 v78, v78
	v_exp_f32_e32 v79, v79
	v_add_f32_e32 v208, v246, v208
	v_add_f32_e32 v208, v247, v208
	s_waitcnt lgkmcnt(6)
	v_mfma_f32_32x32x16_bf16 v[48:63], v[114:117], v[142:145], v[48:63]
	v_add_u32_e32 v64, s1, v210
	v_add_f32_e32 v208, v76, v208
	v_add_f32_e32 v208, v77, v208
	v_cvt_pk_bf16_f32 v114, v118, v119
	v_cvt_pk_bf16_f32 v115, v120, v121
	v_cvt_pk_bf16_f32 v116, v122, v123
	v_cvt_pk_bf16_f32 v117, v124, v125
	s_waitcnt lgkmcnt(4)
	v_mfma_f32_32x32x16_bf16 v[48:63], v[130:133], v[126:129], v[48:63]
	v_add_f32_e32 v208, v78, v208
	v_add_f32_e32 v208, v79, v208
	v_permlane32_swap_b32_e32 v114, v116
	v_permlane32_swap_b32_e32 v115, v117
	v_cvt_pk_bf16_f32 v130, v244, v245
	v_cvt_pk_bf16_f32 v131, v246, v247
	v_cvt_pk_bf16_f32 v132, v76, v77
	v_cvt_pk_bf16_f32 v133, v78, v79
	ds_write_b128 v64, v[114:117]
	s_nop 0
	v_permlane32_swap_b32_e32 v130, v132
	v_permlane32_swap_b32_e32 v131, v133
	ds_write_b128 v64, v[130:133] offset:16
	s_add_i32 s40, s40, 1
	s_add_i32 s0, s0, 64
	s_add_i32 s25, s25, 0x8000
	s_add_i32 s100, s0, -1
	s_cmp_ge_i32 s100, s33
	s_cselect_b32 s100, 1, 0
	s_sub_i32 s101, s0, 64
	s_cmp_le_i32 s101, s35
	s_cselect_b32 s101, 1, 0
	s_and_b32 s100, s100, s101
	s_cmp_eq_u32 s83, s40
	s_waitcnt vmcnt(0) lgkmcnt(0)
	s_barrier
	v_mfma_f32_32x32x16_bf16 v[48:63], v[162:165], v[134:137], v[48:63]
	v_mfma_f32_32x32x16_bf16 v[48:63], v[166:169], v[68:71], v[48:63]
	s_cbranch_scc1 .LBB0_303
	s_cmp_lg_u32 s100, 0
	s_cbranch_scc1 .Lgen1
	s_branch .Lfast1
